# PROJ unit order: row-major (1-row groups, each XCD sweeps all 20 column tiles of a row tile) (run 1)
# speedup vs baseline: 1.0113x; 1.0006x over previous
;     __device__ bool next(int i, Unit& u) const { if (r0 + i >= r1) return false; return base.next(r0 + i, u); }
;     __device__ bool next(int i, Unit& u) const { const int L = i * G + c; if (L >= 256) return false; u.pm = L; u.pn = L >> 3; return true; }
;     __device__ bool next(int i, Unit& u) const {
;         const long L = (long)i * G + c; if (L >= nwg) return false;
;         int wgid = (int)L; { const int q = nwg / NXCD, r = nwg % NXCD, xcd = wgid % NXCD, off = wgid / NXCD; wgid = (xcd < r ? xcd * (q + 1) : r * (q + 1) + (xcd - r) * q) + off; }
;         const int nig = WGM * nN, gid = wgid / nig, fm = gid * WGM, gsz = (nM - fm) < WGM ? (nM - fm) : WGM;
;         u.pm = fm + ((wgid % nig) % gsz); u.pn = (wgid % nig) / gsz; return true;
.LBB0_240:
	v_readlane_b32 s8, v255, 3
	s_cmp_lt_i32 s8, 2
	s_cselect_b64 s[6:7], -1, 0
	s_and_b64 s[16:17], s[6:7], s[4:5]
	s_andn2_b64 vcc, exec, s[16:17]
	v_readlane_b32 s9, v255, 4
	v_readlane_b32 s10, v255, 5
	v_readlane_b32 s11, v255, 6
	s_cbranch_vccnz .LBB0_597
	v_readlane_b32 s2, v255, 9
	s_cmpk_lt_i32 s66, 0xa00
	v_mbcnt_lo_u32_b32 v0, -1, 0
	v_mbcnt_hi_u32_b32 v0, -1, v0
	s_cselect_b64 s[4:5], -1, 0
	v_add_u32_e32 v8, s2, v0
	s_cmpk_gt_i32 s66, 0x9ff
	s_cbranch_scc1 .LBB0_243
	s_ashr_i32 s2, s66, 31
	s_lshr_b32 s2, s2, 29
	s_add_i32 s2, s66, s2
	s_ashr_i32 s6, s2, 3
	s_and_b32 s2, s2, -8
	s_sub_i32 s2, s66, s2
	s_cmp_lt_i32 s2, 0
	s_movk_i32 s7, 0x141
	s_cselect_b32 s7, s7, 0x140
	s_mul_i32 s2, s2, s7
	s_add_i32 s2, s2, s6
	s_mul_hi_i32 s6, s2, 0x66666667
	s_lshr_b32 s7, s6, 31
	s_ashr_i32 s6, s6, 3
	s_add_i32 s6, s6, s7
	s_lshl_b32 s7, s6, 0
	s_mulk_i32 s6, 0x14
	s_sub_i32 s2, s2, s6
	s_and_b32 s9, s2, 0
	s_add_i32 s8, s7, s9
	s_lshr_b32 s6, s2, 0

;     __device__ bool next(int i, Unit& u) const { if (r0 + i >= r1) return false; return base.next(r0 + i, u); }
;     __device__ bool next(int i, Unit& u) const { const int L = i * G + c; if (L >= 256) return false; u.pm = L; u.pn = L >> 3; return true; }
;     __device__ bool next(int i, Unit& u) const {
;         const long L = (long)i * G + c; if (L >= nwg) return false;
;         int wgid = (int)L; { const int q = nwg / NXCD, r = nwg % NXCD, xcd = wgid % NXCD, off = wgid / NXCD; wgid = (xcd < r ? xcd * (q + 1) : r * (q + 1) + (xcd - r) * q) + off; }
;         const int nig = WGM * nN, gid = wgid / nig, fm = gid * WGM, gsz = (nM - fm) < WGM ? (nM - fm) : WGM;
;         u.pm = fm + ((wgid % nig) % gsz); u.pn = (wgid % nig) / gsz; return true;
.LBB0_249:
	s_add_i32 s77, s77, 1
	s_mul_i32 s2, s77, s64
	s_mul_hi_u32 s4, s77, s65
	s_add_i32 s4, s4, s2
	s_mul_i32 s2, s77, s65
	v_readlane_b32 s14, v255, 7
	v_readlane_b32 s15, v255, 8
	s_add_u32 s14, s2, s14
	s_addc_u32 s15, s4, s66
	v_cmp_gt_i64_e32 vcc, s[14:15], v[164:165]
	v_cmp_lt_i64_e64 s[4:5], s[14:15], v[162:163]
	s_cbranch_vccnz .LBB0_251
	s_ashr_i32 s2, s14, 31
	s_lshr_b32 s2, s2, 29
	s_add_i32 s2, s14, s2
	s_ashr_i32 s7, s2, 3
	s_and_b32 s2, s2, -8
	s_sub_i32 s2, s14, s2
	s_cmp_lt_i32 s2, 0
	s_movk_i32 s9, 0x141
	s_cselect_b32 s9, s9, 0x140
	s_mul_i32 s2, s2, s9
	s_add_i32 s2, s2, s7
	s_mul_hi_i32 s7, s2, 0x66666667
	s_lshr_b32 s9, s7, 31
	s_ashr_i32 s7, s7, 3
	s_add_i32 s7, s7, s9
	s_lshl_b32 s9, s7, 0
	s_mulk_i32 s7, 0x14
	s_sub_i32 s2, s2, s7
	s_lshr_b32 s38, s2, 0
	s_and_b32 s2, s2, 0
	s_add_i32 s44, s9, s2
